# norm phase row loop software-pipelined (two rows of loads in flight per wave, compiled arithmetic kept); final tile loop 8 row groups in flight
# baseline (speedup 1.0000x reference)
; __device__ __forceinline__ float shx(float v, int mask, int lane) { return __builtin_bit_cast(float, __builtin_amdgcn_ds_bpermute((lane ^ mask) << 2, __builtin_bit_cast(int, v))); }
; __device__ __forceinline__ void phase_norm(int l, int vcu, int G) {
;     ...
;     const int gw = vcu * NWAVES + wave, NGW = G * NWAVES;
;     for (int m = gw; m < MROWS; m += NGW) {
;         const float* xr = xin + (size_t)m * DMODEL + 8 * lane;
;         f32x4 v[2][2]; float s = 0.f;
; #pragma unroll
;         for (int j = 0; j < 2; ++j) { v[j][0] = *(const f32x4*)(xr + 512 * j); v[j][1] = *(const f32x4*)(xr + 512 * j + 4); }
;         if (l > 0) {
;             const bf16r* dr = DL + (size_t)m * DIN;
; #pragma unroll
;             for (int j = 0; j < 2; ++j) { const v4u d = *(const v4u*)(dr + d0_col(512 * j + 8 * lane));
;                 v[j][0].x += bflo(d.x); v[j][0].y += bfhi(d.x); v[j][0].z += bflo(d.y); v[j][0].w += bfhi(d.y); v[j][1].x += bflo(d.z); v[j][1].y += bfhi(d.z); v[j][1].z += bflo(d.w); v[j][1].w += bfhi(d.w); }
;         }
; #pragma unroll
;         for (int j = 0; j < 2; ++j)
; #pragma unroll
;             for (int h = 0; h < 2; ++h) s += (v[j][h].x * v[j][h].x + v[j][h].y * v[j][h].y) + (v[j][h].z * v[j][h].z + v[j][h].w * v[j][h].w);
; #pragma unroll
;         for (int o = 1; o < 64; o <<= 1) s += shx(s, o, lane);
;         const float rstd = rsqrtf(s * (1.f / DMODEL) + EPS);
;         const float* mb = mod + (m >> 12) * 3072;
; #pragma unroll
;         for (int j = 0; j < 2; ++j) { const int col = 512 * j + 8 * lane; f32x4 hh[2];
; #pragma unroll
;             for (int h = 0; h < 2; ++h) { const f32x4 gg = *(const f32x4*)(g + col + 4 * h), sh = *(const f32x4*)(mb + col + 4 * h), sc = *(const f32x4*)(mb + 1024 + col + 4 * h);
.LBB0_169:
	v_writelane_b32 v247, s2, 61
	s_xor_b64 s[0:1], s[2:3], -1
	v_mov_b32_e32 v0, v218
	v_writelane_b32 v247, s3, 62
	v_writelane_b32 v247, s0, 63
	s_mov_b64 s[34:35], s[90:91]
	s_nop 0
	v_writelane_b32 v246, s1, 0
	v_readfirstlane_b32 s0, v0
	s_ashr_i32 s0, s0, 6
	v_readlane_b32 s1, v248, 0
	s_add_i32 s0, s0, s1
	s_cmp_lt_i32 s0, 0x8000
	s_cbranch_scc0 .LBB0_174
	s_load_dwordx2 s[16:17], s[34:35], 0xd8
	s_mul_i32 s20, s76, 0x6000
	s_load_dwordx2 s[14:15], s[34:35], 0x0
	s_load_dwordx2 s[28:29], s[34:35], 0x10
	s_lshl_b64 s[2:3], s[20:21], 2
	v_and_b32_e32 v3, 63, v0
	s_waitcnt lgkmcnt(0)
	s_add_u32 s2, s16, s2
	s_addc_u32 s3, s17, s3
	s_lshl_b32 s20, s76, 10
	s_lshl_b64 s[34:35], s[20:21], 2
	v_lshlrev_b32_e32 v2, 3, v3
	s_add_u32 s28, s28, s34
	v_cmp_gt_u32_e32 vcc, 48, v3
	v_or_b32_e32 v4, 0x200, v2
	s_movk_i32 s1, 0x380
	v_lshlrev_b32_e32 v0, 2, v3
	s_addc_u32 s29, s29, s35
	v_cndmask_b32_e64 v5, v223, 0, vcc
	v_cmp_gt_u32_e32 vcc, s1, v4
	v_xor_b32_e32 v28, 4, v0
	v_xor_b32_e32 v29, 8, v0
	v_xor_b32_e32 v30, 16, v0
	v_xor_b32_e32 v31, 32, v0
	v_xor_b32_e32 v32, 64, v0
	v_xor_b32_e32 v33, 0x80, v0
	v_lshlrev_b32_e32 v0, 5, v3
	s_ashr_i32 s1, s0, 31
	s_mul_i32 s33, s0, 0x1e00
	v_cndmask_b32_e32 v6, v224, v223, vcc
	v_lshl_add_u64 v[18:19], s[28:29], 0, v[0:1]
	s_mul_hi_i32 s20, s0, 0x1e00
	s_add_u32 s28, s33, 0x6000400
	s_addc_u32 s29, s20, 0
	v_add_lshl_u32 v6, v6, v2, 1
	v_mov_b32_e32 v7, v1
	v_lshl_add_u64 v[20:21], s[28:29], 0, v[6:7]
	s_add_u32 s28, s33, 0x6000000
	s_addc_u32 s29, s20, 0
	v_add_lshl_u32 v6, v5, v2, 1
	v_lshl_add_u64 v[22:23], s[28:29], 0, v[6:7]
	s_lshl_b64 s[28:29], s[0:1], 11
	v_lshl_or_b32 v24, v3, 4, s28
	v_mov_b32_e32 v25, s29
	s_lshl_b64 s[28:29], s[0:1], 12
	s_add_u32 s14, s14, s28
	s_addc_u32 s15, s15, s29
	v_lshl_add_u64 v[6:7], s[14:15], 0, v[0:1]
	s_mov_b64 s[14:15], 0x800
	v_lshl_add_u64 v[26:27], v[6:7], 0, s[14:15]
	v_lshlrev_b32_e32 v0, 2, v2
	v_lshlrev_b32_e32 v34, 2, v4
	v_readlane_b32 s14, v247, 63
	v_readlane_b32 s28, v247, 42
	v_readlane_b32 s29, v247, 43
	v_readlane_b32 s98, v247, 19
	v_readlane_b32 s99, v247, 20
	s_cmp_lg_u32 s14, 0
	s_cselect_b32 s20, 1, 0
	s_mov_b32 s33, s0
	global_load_dwordx4 v[202:205], v[18:19], off
	global_load_dwordx4 v[206:209], v[18:19], off offset:16
	global_load_dwordx4 v[210:213], v[18:19], off offset:2048
	global_load_dwordx4 v[214:217], v[18:19], off offset:2064
	v_mov_b64_e32 v[228:229], v[26:27]
	v_lshl_add_u64 v[230:231], s[16:17], 0, v[22:23]
	v_lshl_add_u64 v[232:233], s[16:17], 0, v[20:21]
	global_load_dwordx4 v[68:71], v[228:229], off offset:-2048
	global_load_dwordx4 v[72:75], v[228:229], off offset:-2032
	global_load_dwordx4 v[76:79], v[228:229], off
	global_load_dwordx4 v[80:83], v[228:229], off offset:16
	s_cmp_lg_u32 s20, 0
	s_cbranch_scc0 .Lnorm_pf_nod_1
	global_load_dwordx4 v[84:87], v[230:231], off
	global_load_dwordx4 v[88:91], v[232:233], off
.Lnorm_pf_nod_1:
	s_ashr_i32 s14, s33, 12
	s_mul_i32 s14, s14, 0x3000
	s_add_u32 s34, s2, s14
	s_addc_u32 s35, s3, 0
	s_add_u32 s40, s34, 0x1000
	s_addc_u32 s41, s35, 0
	global_load_dwordx4 v[92:95], v0, s[40:41]
	global_load_dwordx4 v[96:99], v0, s[40:41] offset:16
	global_load_dwordx4 v[100:103], v0, s[40:41] offset:2048
	global_load_dwordx4 v[104:107], v0, s[40:41] offset:2064
	global_load_dwordx4 v[108:111], v0, s[34:35]
	global_load_dwordx4 v[112:115], v0, s[34:35] offset:16
	global_load_dwordx4 v[116:119], v0, s[34:35] offset:2048
	global_load_dwordx4 v[120:123], v0, s[34:35] offset:2064
	s_add_i32 s14, s33, s86
	s_cmp_lt_i32 s14, 0x8000
	s_cselect_b32 s33, s14, s33
	s_cselect_b64 s[14:15], s[28:29], 0
	v_lshl_add_u64 v[228:229], v[228:229], 0, s[14:15]
	s_cselect_b64 s[14:15], s[98:99], 0
	v_lshl_add_u64 v[230:231], v[230:231], 0, s[14:15]
	v_lshl_add_u64 v[232:233], v[232:233], 0, s[14:15]
	global_load_dwordx4 v[124:127], v[228:229], off offset:-2048
	global_load_dwordx4 v[128:131], v[228:229], off offset:-2032
	global_load_dwordx4 v[132:135], v[228:229], off
	global_load_dwordx4 v[136:139], v[228:229], off offset:16
	s_cmp_lg_u32 s20, 0
	s_cbranch_scc0 .Lnorm_pf_nod_2
	global_load_dwordx4 v[140:143], v[230:231], off
	global_load_dwordx4 v[144:147], v[232:233], off
.Lnorm_pf_nod_2:
	s_ashr_i32 s14, s33, 12
	s_mul_i32 s14, s14, 0x3000
	s_add_u32 s34, s2, s14
	s_addc_u32 s35, s3, 0
	s_add_u32 s40, s34, 0x1000
	s_addc_u32 s41, s35, 0
	global_load_dwordx4 v[148:151], v0, s[40:41]
	global_load_dwordx4 v[152:155], v0, s[40:41] offset:16
	global_load_dwordx4 v[156:159], v0, s[40:41] offset:2048
	global_load_dwordx4 v[160:163], v0, s[40:41] offset:2064
	global_load_dwordx4 v[164:167], v0, s[34:35]
	global_load_dwordx4 v[168:171], v0, s[34:35] offset:16
	global_load_dwordx4 v[172:175], v0, s[34:35] offset:2048
	global_load_dwordx4 v[176:179], v0, s[34:35] offset:2064
	s_add_i32 s14, s33, s86
	s_cmp_lt_i32 s14, 0x8000
	s_cselect_b32 s33, s14, s33
	s_cselect_b64 s[14:15], s[28:29], 0
	v_lshl_add_u64 v[228:229], v[228:229], 0, s[14:15]
	s_cselect_b64 s[14:15], s[98:99], 0
	v_lshl_add_u64 v[230:231], v[230:231], 0, s[14:15]
	v_lshl_add_u64 v[232:233], v[232:233], 0, s[14:15]
	s_cmp_lg_u32 s20, 0
	s_cbranch_scc1 .Lnorm_w_first_l1
	s_waitcnt vmcnt(12)
	s_branch .Lnorm_w_first_done
.Lnorm_w_first_l1:
	s_waitcnt vmcnt(14)
.Lnorm_w_first_done:
	s_branch .Lnorm_body_P
.Lnorm_loop:
	s_cmp_lg_u32 s20, 0
	s_cbranch_scc1 .Lnorm_w_P_l1
	s_waitcnt vmcnt(15)
	s_branch .Lnorm_w_P_done
.Lnorm_w_P_l1:
	s_waitcnt vmcnt(17)
; __device__ __forceinline__ unsigned pk2(float lo, float hi) { return f2bf(lo) | (f2bf(hi) << 16); }
; __device__ __forceinline__ float shx(float v, int mask, int lane) { return __builtin_bit_cast(float, __builtin_amdgcn_ds_bpermute((lane ^ mask) << 2, __builtin_bit_cast(int, v))); }
; __device__ __forceinline__ void phase_norm(int l, int vcu, int G) {
;     ...
;         if (l > 0) {
;             const bf16r* dr = DL + (size_t)m * DIN;
; #pragma unroll
;             for (int j = 0; j < 2; ++j) { const v4u d = *(const v4u*)(dr + d0_col(512 * j + 8 * lane));
;                 v[j][0].x += bflo(d.x); v[j][0].y += bfhi(d.x); v[j][0].z += bflo(d.y); v[j][0].w += bfhi(d.y); v[j][1].x += bflo(d.z); v[j][1].y += bfhi(d.z); v[j][1].z += bflo(d.w); v[j][1].w += bfhi(d.w); }
;         }
; #pragma unroll
;         for (int j = 0; j < 2; ++j)
; #pragma unroll
;             for (int h = 0; h < 2; ++h) s += (v[j][h].x * v[j][h].x + v[j][h].y * v[j][h].y) + (v[j][h].z * v[j][h].z + v[j][h].w * v[j][h].w);
; #pragma unroll
;         for (int o = 1; o < 64; o <<= 1) s += shx(s, o, lane);
;         const float rstd = rsqrtf(s * (1.f / DMODEL) + EPS);
;         const float* mb = mod + (m >> 12) * 3072;
; #pragma unroll
;         for (int j = 0; j < 2; ++j) { const int col = 512 * j + 8 * lane; f32x4 hh[2];
; #pragma unroll
;             for (int h = 0; h < 2; ++h) { const f32x4 gg = *(const f32x4*)(g + col + 4 * h), sh = *(const f32x4*)(mb + col + 4 * h), sc = *(const f32x4*)(mb + 1024 + col + 4 * h);
;                 hh[h] = v[j][h] * rstd * gg * (sc + 1.0f) + sh; }
;             v4u o; o.x = pk2(hh[0].x, hh[0].y); o.y = pk2(hh[0].z, hh[0].w); o.z = pk2(hh[1].x, hh[1].y); o.w = pk2(hh[1].z, hh[1].w);
;             *(v4u*)(H + (size_t)m * DMODEL + col) = o; }
.Lnorm_w_P_done:
.Lnorm_body_P:
	v_mov_b64_e32 v[10:11], v[72:73]
	v_mov_b64_e32 v[12:13], v[74:75]
	v_mov_b64_e32 v[14:15], v[68:69]
	v_mov_b64_e32 v[16:17], v[70:71]
	v_mov_b64_e32 v[2:3], v[80:81]
	v_mov_b64_e32 v[4:5], v[82:83]
	v_mov_b64_e32 v[6:7], v[76:77]
	v_mov_b64_e32 v[8:9], v[78:79]
	v_readlane_b32 s14, v247, 63
	v_readlane_b32 s15, v246, 0
	s_andn2_b64 vcc, exec, s[14:15]
	s_cbranch_vccnz .Lnorm_main_P
	v_mov_b64_e32 v[36:37], v[84:85]
	v_mov_b64_e32 v[38:39], v[86:87]
	v_mov_b64_e32 v[40:41], v[88:89]
	v_mov_b64_e32 v[42:43], v[90:91]
	v_lshlrev_b32_e32 v44, 16, v36
	v_and_b32_e32 v45, 0xffff0000, v36
	v_lshlrev_b32_e32 v36, 16, v37
	v_and_b32_e32 v37, 0xffff0000, v37
	v_lshlrev_b32_e32 v46, 16, v38
	v_and_b32_e32 v47, 0xffff0000, v38
	v_lshlrev_b32_e32 v38, 16, v39
	v_and_b32_e32 v39, 0xffff0000, v39
	v_lshlrev_b32_e32 v48, 16, v40
	v_and_b32_e32 v49, 0xffff0000, v40
	v_lshlrev_b32_e32 v40, 16, v41
	v_and_b32_e32 v41, 0xffff0000, v41
	v_lshlrev_b32_e32 v50, 16, v42
	v_and_b32_e32 v51, 0xffff0000, v42
	v_lshlrev_b32_e32 v42, 16, v43
	v_and_b32_e32 v43, 0xffff0000, v43
	v_pk_add_f32 v[14:15], v[14:15], v[44:45]
	v_pk_add_f32 v[16:17], v[16:17], v[36:37]
	v_pk_add_f32 v[10:11], v[10:11], v[46:47]
	v_pk_add_f32 v[12:13], v[12:13], v[38:39]
	v_pk_add_f32 v[6:7], v[6:7], v[48:49]
	v_pk_add_f32 v[8:9], v[8:9], v[40:41]
	v_pk_add_f32 v[2:3], v[2:3], v[50:51]
	v_pk_add_f32 v[4:5], v[4:5], v[42:43]
.Lnorm_main_P:
	v_mov_b64_e32 v[36:37], v[206:207]
	v_mov_b64_e32 v[38:39], v[208:209]
	v_mov_b64_e32 v[40:41], v[202:203]
	v_mov_b64_e32 v[42:43], v[204:205]
	v_mov_b64_e32 v[44:45], v[96:97]
	v_mov_b64_e32 v[46:47], v[98:99]
	v_mov_b64_e32 v[48:49], v[92:93]
	v_mov_b64_e32 v[50:51], v[94:95]
	v_mov_b64_e32 v[52:53], v[108:109]
	v_mov_b64_e32 v[54:55], v[110:111]
	v_mov_b64_e32 v[56:57], v[112:113]
	v_mov_b64_e32 v[58:59], v[114:115]
	v_pk_mul_f32 v[60:61], v[16:17], v[16:17]
	v_pk_mul_f32 v[62:63], v[14:15], v[14:15]
	s_brev_b32 s1, 64
	v_pk_mov_b32 v[64:65], v[62:63], v[60:61] op_sel:[1,0]
	v_mov_b32_e32 v63, v61
	v_pk_add_f32 v[60:61], v[64:65], v[62:63]
	v_pk_mul_f32 v[62:63], v[12:13], v[12:13]
	v_pk_add_f32 v[60:61], v[60:61], v[60:61] op_sel_hi:[0,1]
	v_pk_mul_f32 v[64:65], v[10:11], v[10:11]
	v_mul_f32_e32 v60, v6, v6
	v_pk_mov_b32 v[66:67], v[64:65], v[62:63] op_sel:[1,0]
	v_mov_b32_e32 v65, v63
	v_pk_add_f32 v[62:63], v[66:67], v[64:65]
	v_pk_fma_f32 v[64:65], v[6:7], v[6:7], v[60:61] op_sel_hi:[1,1,0]
	v_mul_f32_e32 v60, v8, v8
	v_pk_add_f32 v[62:63], v[62:63], v[62:63] op_sel_hi:[0,1]
	v_pk_fma_f32 v[66:67], v[8:9], v[8:9], v[60:61] op_sel_hi:[1,1,0]
	v_mul_f32_e32 v64, v2, v2
	v_mul_f32_e32 v66, v3, v3
	v_mul_f32_e32 v62, v4, v4
	v_mul_f32_e32 v60, v5, v5
	v_pk_add_f32 v[64:65], v[64:65], v[66:67]
	v_pk_add_f32 v[60:61], v[62:63], v[60:61]
	v_pk_add_f32 v[60:61], v[64:65], v[60:61]
	v_add_f32_e32 v35, v60, v61
	ds_bpermute_b32 v60, v28, v35
	v_readlane_b32 s14, v247, 40
	v_readlane_b32 s15, v247, 41
	s_waitcnt lgkmcnt(0)
	v_add_f32_e32 v35, v35, v60
	ds_bpermute_b32 v60, v29, v35
	s_add_i32 s0, s0, s86
	s_waitcnt lgkmcnt(0)
	v_add_f32_e32 v35, v35, v60
	ds_bpermute_b32 v60, v30, v35
	s_waitcnt lgkmcnt(0)
	v_add_f32_e32 v35, v35, v60
	ds_bpermute_b32 v60, v31, v35
	s_waitcnt lgkmcnt(0)
	v_add_f32_e32 v35, v35, v60
	ds_bpermute_b32 v60, v32, v35
	s_waitcnt lgkmcnt(0)
	v_add_f32_e32 v35, v35, v60
	ds_bpermute_b32 v60, v33, v35
	s_waitcnt lgkmcnt(0)
	v_add_f32_e32 v35, v35, v60
	v_fmamk_f32 v35, v35, 0x3a800000, v219
	v_mul_f32_e32 v60, 0x4b800000, v35
	v_cmp_gt_f32_e32 vcc, s25, v35
	s_nop 1
	v_cndmask_b32_e32 v35, v35, v60, vcc
	v_rsq_f32_e32 v35, v35
	s_nop 0
	v_mul_f32_e32 v60, 0x45800000, v35
	v_cndmask_b32_e32 v60, v35, v60, vcc
	v_pk_mul_f32 v[10:11], v[10:11], v[60:61] op_sel_hi:[1,0]
	v_pk_mul_f32 v[16:17], v[16:17], v[60:61] op_sel_hi:[1,0]
	v_pk_mul_f32 v[14:15], v[14:15], v[60:61] op_sel_hi:[1,0]
	v_pk_mul_f32 v[12:13], v[12:13], v[60:61] op_sel_hi:[1,0]
	v_pk_mul_f32 v[14:15], v[40:41], v[14:15]
	v_pk_mul_f32 v[16:17], v[42:43], v[16:17]
	v_pk_mul_f32 v[10:11], v[36:37], v[10:11]
	v_pk_add_f32 v[36:37], v[50:51], 1.0 op_sel_hi:[1,0]
	v_pk_add_f32 v[40:41], v[48:49], 1.0 op_sel_hi:[1,0]
	v_pk_mul_f32 v[12:13], v[38:39], v[12:13]
	v_pk_add_f32 v[38:39], v[46:47], 1.0 op_sel_hi:[1,0]
	v_pk_add_f32 v[42:43], v[44:45], 1.0 op_sel_hi:[1,0]
	v_pk_fma_f32 v[16:17], v[36:37], v[16:17], v[54:55]
	v_pk_fma_f32 v[14:15], v[40:41], v[14:15], v[52:53]
	v_pk_fma_f32 v[12:13], v[38:39], v[12:13], v[58:59]
	v_pk_fma_f32 v[10:11], v[42:43], v[10:11], v[56:57]
	v_bfe_u32 v35, v14, 16, 1
	v_bfe_u32 v37, v16, 16, 1
	v_bfe_u32 v38, v17, 16, 1
	v_bfe_u32 v40, v11, 16, 1
	v_bfe_u32 v41, v12, 16, 1
	v_add3_u32 v14, v14, v35, s72
	v_add3_u32 v16, v16, v37, s72
	v_bfe_u32 v36, v15, 16, 1
	v_bfe_u32 v39, v10, 16, 1
	v_add3_u32 v17, v17, v38, s72
	v_add3_u32 v35, v11, v40, s72
	v_add3_u32 v11, v12, v41, s72
	v_lshrrev_b32_e32 v12, 16, v14
	v_lshrrev_b32_e32 v14, 16, v16
	v_add3_u32 v15, v15, v36, s72
	v_add3_u32 v10, v10, v39, s72
	v_lshrrev_b32_e32 v36, 16, v11
	v_and_or_b32 v11, v17, s55, v14
	v_bfe_u32 v14, v13, 16, 1
	v_lshrrev_b32_e32 v16, 16, v10
	v_and_or_b32 v10, v15, s55, v12
	v_add3_u32 v13, v13, v14, s72
	v_lshl_add_u64 v[14:15], s[16:17], 0, v[24:25]
	v_add_co_u32_e32 v52, vcc, s1, v14
	v_and_or_b32 v12, v35, s55, v16
	v_and_or_b32 v13, v13, s55, v36
	v_addc_co_u32_e32 v53, vcc, 0, v15, vcc
	global_store_dwordx4 v[52:53], v[10:13], off
	v_mov_b64_e32 v[36:37], v[210:211]
	v_mov_b64_e32 v[38:39], v[212:213]
	v_mov_b64_e32 v[40:41], v[214:215]
	v_mov_b64_e32 v[42:43], v[216:217]
	v_mov_b64_e32 v[44:45], v[120:121]
	v_mov_b64_e32 v[46:47], v[122:123]
	v_mov_b64_e32 v[48:49], v[116:117]
	v_mov_b64_e32 v[50:51], v[118:119]
	v_mov_b64_e32 v[10:11], v[100:101]
	v_mov_b64_e32 v[12:13], v[102:103]
	v_mov_b64_e32 v[14:15], v[104:105]
	v_mov_b64_e32 v[16:17], v[106:107]
	v_pk_mul_f32 v[4:5], v[4:5], v[60:61] op_sel_hi:[1,0]
	v_pk_mul_f32 v[2:3], v[2:3], v[60:61] op_sel_hi:[1,0]
	v_pk_mul_f32 v[8:9], v[8:9], v[60:61] op_sel_hi:[1,0]
	v_pk_mul_f32 v[6:7], v[6:7], v[60:61] op_sel_hi:[1,0]
	v_lshl_add_u64 v[24:25], v[24:25], 0, s[14:15]
	global_load_dwordx4 v[68:71], v[228:229], off offset:-2048
	global_load_dwordx4 v[72:75], v[228:229], off offset:-2032
	global_load_dwordx4 v[76:79], v[228:229], off
	global_load_dwordx4 v[80:83], v[228:229], off offset:16
	s_cmp_lg_u32 s20, 0
	s_cbranch_scc0 .Lnorm_pf_nod_3
	global_load_dwordx4 v[84:87], v[230:231], off
	global_load_dwordx4 v[88:91], v[232:233], off
; __device__ __forceinline__ unsigned pk2(float lo, float hi) { return f2bf(lo) | (f2bf(hi) << 16); }
; __device__ __forceinline__ float shx(float v, int mask, int lane) { return __builtin_bit_cast(float, __builtin_amdgcn_ds_bpermute((lane ^ mask) << 2, __builtin_bit_cast(int, v))); }
; __device__ __forceinline__ void phase_norm(int l, int vcu, int G) {
;     ...
;         if (l > 0) {
;             const bf16r* dr = DL + (size_t)m * DIN;
; #pragma unroll
;             for (int j = 0; j < 2; ++j) { const v4u d = *(const v4u*)(dr + d0_col(512 * j + 8 * lane));
;                 v[j][0].x += bflo(d.x); v[j][0].y += bfhi(d.x); v[j][0].z += bflo(d.y); v[j][0].w += bfhi(d.y); v[j][1].x += bflo(d.z); v[j][1].y += bfhi(d.z); v[j][1].z += bflo(d.w); v[j][1].w += bfhi(d.w); }
;         }
; #pragma unroll
;         for (int j = 0; j < 2; ++j)
; #pragma unroll
;             for (int h = 0; h < 2; ++h) s += (v[j][h].x * v[j][h].x + v[j][h].y * v[j][h].y) + (v[j][h].z * v[j][h].z + v[j][h].w * v[j][h].w);
; #pragma unroll
;         for (int o = 1; o < 64; o <<= 1) s += shx(s, o, lane);
;         const float rstd = rsqrtf(s * (1.f / DMODEL) + EPS);
;         const float* mb = mod + (m >> 12) * 3072;
; #pragma unroll
;         for (int j = 0; j < 2; ++j) { const int col = 512 * j + 8 * lane; f32x4 hh[2];
; #pragma unroll
;             for (int h = 0; h < 2; ++h) { const f32x4 gg = *(const f32x4*)(g + col + 4 * h), sh = *(const f32x4*)(mb + col + 4 * h), sc = *(const f32x4*)(mb + 1024 + col + 4 * h);
;                 hh[h] = v[j][h] * rstd * gg * (sc + 1.0f) + sh; }
;             v4u o; o.x = pk2(hh[0].x, hh[0].y); o.y = pk2(hh[0].z, hh[0].w); o.z = pk2(hh[1].x, hh[1].y); o.w = pk2(hh[1].z, hh[1].w);
;             *(v4u*)(H + (size_t)m * DMODEL + col) = o; }
.Lnorm_pf_nod_3:
	s_ashr_i32 s14, s33, 12
	s_mul_i32 s14, s14, 0x3000
	s_add_u32 s34, s2, s14
	s_addc_u32 s35, s3, 0
	s_add_u32 s40, s34, 0x1000
	s_addc_u32 s41, s35, 0
	global_load_dwordx4 v[92:95], v0, s[40:41]
	global_load_dwordx4 v[96:99], v0, s[40:41] offset:16
	global_load_dwordx4 v[100:103], v0, s[40:41] offset:2048
	global_load_dwordx4 v[104:107], v0, s[40:41] offset:2064
	global_load_dwordx4 v[108:111], v0, s[34:35]
	global_load_dwordx4 v[112:115], v0, s[34:35] offset:16
	global_load_dwordx4 v[116:119], v0, s[34:35] offset:2048
	global_load_dwordx4 v[120:123], v0, s[34:35] offset:2064
	s_add_i32 s14, s33, s86
	s_cmp_lt_i32 s14, 0x8000
	s_cselect_b32 s33, s14, s33
	s_cselect_b64 s[14:15], s[28:29], 0
	v_lshl_add_u64 v[228:229], v[228:229], 0, s[14:15]
	s_cselect_b64 s[14:15], s[98:99], 0
	v_lshl_add_u64 v[230:231], v[230:231], 0, s[14:15]
	v_lshl_add_u64 v[232:233], v[232:233], 0, s[14:15]
	v_pk_add_f32 v[12:13], v[12:13], 1.0 op_sel_hi:[1,0]
	v_pk_add_f32 v[16:17], v[16:17], 1.0 op_sel_hi:[1,0]
	v_pk_add_f32 v[10:11], v[10:11], 1.0 op_sel_hi:[1,0]
	v_pk_add_f32 v[14:15], v[14:15], 1.0 op_sel_hi:[1,0]
	v_pk_mul_f32 v[6:7], v[36:37], v[6:7]
	v_pk_mul_f32 v[8:9], v[38:39], v[8:9]
	v_pk_mul_f32 v[2:3], v[40:41], v[2:3]
	v_pk_mul_f32 v[4:5], v[42:43], v[4:5]
	v_pk_fma_f32 v[2:3], v[14:15], v[2:3], v[44:45]
	v_pk_fma_f32 v[4:5], v[16:17], v[4:5], v[46:47]
	v_pk_fma_f32 v[8:9], v[12:13], v[8:9], v[50:51]
	v_pk_fma_f32 v[6:7], v[10:11], v[6:7], v[48:49]
	v_bfe_u32 v12, v8, 16, 1
	v_bfe_u32 v10, v6, 16, 1
	v_bfe_u32 v14, v2, 16, 1
	v_bfe_u32 v15, v3, 16, 1
	v_bfe_u32 v16, v4, 16, 1
	v_bfe_u32 v11, v7, 16, 1
	v_bfe_u32 v13, v9, 16, 1
	v_bfe_u32 v17, v5, 16, 1
	v_add3_u32 v6, v6, v10, s72
	v_add3_u32 v8, v8, v12, s72
	v_add3_u32 v2, v2, v14, s72
	v_add3_u32 v10, v3, v15, s72
	v_add3_u32 v3, v4, v16, s72
	v_add3_u32 v7, v7, v11, s72
	v_add3_u32 v9, v9, v13, s72
	v_add3_u32 v5, v5, v17, s72
	v_lshrrev_b32_e32 v4, 16, v6
	v_lshrrev_b32_e32 v6, 16, v8
	v_lshrrev_b32_e32 v8, 16, v2
	v_lshrrev_b32_e32 v11, 16, v3
	v_and_or_b32 v2, v7, s55, v4
	v_and_or_b32 v3, v9, s55, v6
	v_and_or_b32 v4, v10, s55, v8
	v_and_or_b32 v5, v5, s55, v11
	global_store_dwordx4 v[52:53], v[2:5], off offset:1024
	s_cmp_lt_i32 s0, 0x8000
	s_cbranch_scc0 .Lnorm_exit
	s_cmp_lg_u32 s20, 0
	s_cbranch_scc1 .Lnorm_w_Q_l1
	s_waitcnt vmcnt(14)
	s_branch .Lnorm_w_Q_done
.Lnorm_w_Q_l1:
	s_waitcnt vmcnt(16)
.Lnorm_w_Q_done:
	v_mov_b64_e32 v[10:11], v[128:129]
	v_mov_b64_e32 v[12:13], v[130:131]
	v_mov_b64_e32 v[14:15], v[124:125]
	v_mov_b64_e32 v[16:17], v[126:127]
	v_mov_b64_e32 v[2:3], v[136:137]
	v_mov_b64_e32 v[4:5], v[138:139]
	v_mov_b64_e32 v[6:7], v[132:133]
	v_mov_b64_e32 v[8:9], v[134:135]
	v_readlane_b32 s14, v247, 63
	v_readlane_b32 s15, v246, 0
	s_andn2_b64 vcc, exec, s[14:15]
	s_cbranch_vccnz .Lnorm_main_Q
	v_mov_b64_e32 v[36:37], v[140:141]
	v_mov_b64_e32 v[38:39], v[142:143]
	v_mov_b64_e32 v[40:41], v[144:145]
	v_mov_b64_e32 v[42:43], v[146:147]
	v_lshlrev_b32_e32 v44, 16, v36
	v_and_b32_e32 v45, 0xffff0000, v36
	v_lshlrev_b32_e32 v36, 16, v37
	v_and_b32_e32 v37, 0xffff0000, v37
	v_lshlrev_b32_e32 v46, 16, v38
	v_and_b32_e32 v47, 0xffff0000, v38
	v_lshlrev_b32_e32 v38, 16, v39
	v_and_b32_e32 v39, 0xffff0000, v39
	v_lshlrev_b32_e32 v48, 16, v40
	v_and_b32_e32 v49, 0xffff0000, v40
	v_lshlrev_b32_e32 v40, 16, v41
	v_and_b32_e32 v41, 0xffff0000, v41
	v_lshlrev_b32_e32 v50, 16, v42
	v_and_b32_e32 v51, 0xffff0000, v42
	v_lshlrev_b32_e32 v42, 16, v43
	v_and_b32_e32 v43, 0xffff0000, v43
	v_pk_add_f32 v[14:15], v[14:15], v[44:45]
	v_pk_add_f32 v[16:17], v[16:17], v[36:37]
	v_pk_add_f32 v[10:11], v[10:11], v[46:47]
	v_pk_add_f32 v[12:13], v[12:13], v[38:39]
	v_pk_add_f32 v[6:7], v[6:7], v[48:49]
	v_pk_add_f32 v[8:9], v[8:9], v[40:41]
	v_pk_add_f32 v[2:3], v[2:3], v[50:51]
	v_pk_add_f32 v[4:5], v[4:5], v[42:43]
.Lnorm_main_Q:
	v_mov_b64_e32 v[36:37], v[206:207]
	v_mov_b64_e32 v[38:39], v[208:209]
	v_mov_b64_e32 v[40:41], v[202:203]
	v_mov_b64_e32 v[42:43], v[204:205]
	v_mov_b64_e32 v[44:45], v[152:153]
	v_mov_b64_e32 v[46:47], v[154:155]
	v_mov_b64_e32 v[48:49], v[148:149]
	v_mov_b64_e32 v[50:51], v[150:151]
	v_mov_b64_e32 v[52:53], v[164:165]
	v_mov_b64_e32 v[54:55], v[166:167]
	v_mov_b64_e32 v[56:57], v[168:169]
	v_mov_b64_e32 v[58:59], v[170:171]
	v_pk_mul_f32 v[60:61], v[16:17], v[16:17]
	v_pk_mul_f32 v[62:63], v[14:15], v[14:15]
	s_brev_b32 s1, 64
	v_pk_mov_b32 v[64:65], v[62:63], v[60:61] op_sel:[1,0]
	v_mov_b32_e32 v63, v61
	v_pk_add_f32 v[60:61], v[64:65], v[62:63]
	v_pk_mul_f32 v[62:63], v[12:13], v[12:13]
	v_pk_add_f32 v[60:61], v[60:61], v[60:61] op_sel_hi:[0,1]
	v_pk_mul_f32 v[64:65], v[10:11], v[10:11]
	v_mul_f32_e32 v60, v6, v6
	v_pk_mov_b32 v[66:67], v[64:65], v[62:63] op_sel:[1,0]
	v_mov_b32_e32 v65, v63
	v_pk_add_f32 v[62:63], v[66:67], v[64:65]
	v_pk_fma_f32 v[64:65], v[6:7], v[6:7], v[60:61] op_sel_hi:[1,1,0]
	v_mul_f32_e32 v60, v8, v8
	v_pk_add_f32 v[62:63], v[62:63], v[62:63] op_sel_hi:[0,1]
	v_pk_fma_f32 v[66:67], v[8:9], v[8:9], v[60:61] op_sel_hi:[1,1,0]
	v_mul_f32_e32 v64, v2, v2
	v_mul_f32_e32 v66, v3, v3
	v_mul_f32_e32 v62, v4, v4
	v_mul_f32_e32 v60, v5, v5
	v_pk_add_f32 v[64:65], v[64:65], v[66:67]
	v_pk_add_f32 v[60:61], v[62:63], v[60:61]
	v_pk_add_f32 v[60:61], v[64:65], v[60:61]
	v_add_f32_e32 v35, v60, v61
	ds_bpermute_b32 v60, v28, v35
	v_readlane_b32 s14, v247, 40
	v_readlane_b32 s15, v247, 41
	s_waitcnt lgkmcnt(0)
	v_add_f32_e32 v35, v35, v60
	ds_bpermute_b32 v60, v29, v35
	s_add_i32 s0, s0, s86
	s_waitcnt lgkmcnt(0)
	v_add_f32_e32 v35, v35, v60
	ds_bpermute_b32 v60, v30, v35
	s_waitcnt lgkmcnt(0)
	v_add_f32_e32 v35, v35, v60
	ds_bpermute_b32 v60, v31, v35
	s_waitcnt lgkmcnt(0)
; __device__ __forceinline__ unsigned pk2(float lo, float hi) { return f2bf(lo) | (f2bf(hi) << 16); }
; __device__ __forceinline__ float shx(float v, int mask, int lane) { return __builtin_bit_cast(float, __builtin_amdgcn_ds_bpermute((lane ^ mask) << 2, __builtin_bit_cast(int, v))); }
; __device__ __forceinline__ void phase_norm(int l, int vcu, int G) {
;     ...
;         for (int o = 1; o < 64; o <<= 1) s += shx(s, o, lane);
;         const float rstd = rsqrtf(s * (1.f / DMODEL) + EPS);
;         const float* mb = mod + (m >> 12) * 3072;
; #pragma unroll
;         for (int j = 0; j < 2; ++j) { const int col = 512 * j + 8 * lane; f32x4 hh[2];
; #pragma unroll
;             for (int h = 0; h < 2; ++h) { const f32x4 gg = *(const f32x4*)(g + col + 4 * h), sh = *(const f32x4*)(mb + col + 4 * h), sc = *(const f32x4*)(mb + 1024 + col + 4 * h);
;                 hh[h] = v[j][h] * rstd * gg * (sc + 1.0f) + sh; }
;             v4u o; o.x = pk2(hh[0].x, hh[0].y); o.y = pk2(hh[0].z, hh[0].w); o.z = pk2(hh[1].x, hh[1].y); o.w = pk2(hh[1].z, hh[1].w);
;             *(v4u*)(H + (size_t)m * DMODEL + col) = o; }
; __device__ __forceinline__ void xcd_barrier(const XcdBarrier& b) {
;     asm volatile("s_waitcnt vmcnt(0)" ::: "memory");
;     __syncthreads();
	v_add_f32_e32 v35, v35, v60
	ds_bpermute_b32 v60, v32, v35
	s_waitcnt lgkmcnt(0)
	v_add_f32_e32 v35, v35, v60
	ds_bpermute_b32 v60, v33, v35
	s_waitcnt lgkmcnt(0)
	v_add_f32_e32 v35, v35, v60
	v_fmamk_f32 v35, v35, 0x3a800000, v219
	v_mul_f32_e32 v60, 0x4b800000, v35
	v_cmp_gt_f32_e32 vcc, s25, v35
	s_nop 1
	v_cndmask_b32_e32 v35, v35, v60, vcc
	v_rsq_f32_e32 v35, v35
	s_nop 0
	v_mul_f32_e32 v60, 0x45800000, v35
	v_cndmask_b32_e32 v60, v35, v60, vcc
	v_pk_mul_f32 v[10:11], v[10:11], v[60:61] op_sel_hi:[1,0]
	v_pk_mul_f32 v[16:17], v[16:17], v[60:61] op_sel_hi:[1,0]
	v_pk_mul_f32 v[14:15], v[14:15], v[60:61] op_sel_hi:[1,0]
	v_pk_mul_f32 v[12:13], v[12:13], v[60:61] op_sel_hi:[1,0]
	v_pk_mul_f32 v[14:15], v[40:41], v[14:15]
	v_pk_mul_f32 v[16:17], v[42:43], v[16:17]
	v_pk_mul_f32 v[10:11], v[36:37], v[10:11]
	v_pk_add_f32 v[36:37], v[50:51], 1.0 op_sel_hi:[1,0]
	v_pk_add_f32 v[40:41], v[48:49], 1.0 op_sel_hi:[1,0]
	v_pk_mul_f32 v[12:13], v[38:39], v[12:13]
	v_pk_add_f32 v[38:39], v[46:47], 1.0 op_sel_hi:[1,0]
	v_pk_add_f32 v[42:43], v[44:45], 1.0 op_sel_hi:[1,0]
	v_pk_fma_f32 v[16:17], v[36:37], v[16:17], v[54:55]
	v_pk_fma_f32 v[14:15], v[40:41], v[14:15], v[52:53]
	v_pk_fma_f32 v[12:13], v[38:39], v[12:13], v[58:59]
	v_pk_fma_f32 v[10:11], v[42:43], v[10:11], v[56:57]
	v_bfe_u32 v35, v14, 16, 1
	v_bfe_u32 v37, v16, 16, 1
	v_bfe_u32 v38, v17, 16, 1
	v_bfe_u32 v40, v11, 16, 1
	v_bfe_u32 v41, v12, 16, 1
	v_add3_u32 v14, v14, v35, s72
	v_add3_u32 v16, v16, v37, s72
	v_bfe_u32 v36, v15, 16, 1
	v_bfe_u32 v39, v10, 16, 1
	v_add3_u32 v17, v17, v38, s72
	v_add3_u32 v35, v11, v40, s72
	v_add3_u32 v11, v12, v41, s72
	v_lshrrev_b32_e32 v12, 16, v14
	v_lshrrev_b32_e32 v14, 16, v16
	v_add3_u32 v15, v15, v36, s72
	v_add3_u32 v10, v10, v39, s72
	v_lshrrev_b32_e32 v36, 16, v11
	v_and_or_b32 v11, v17, s55, v14
	v_bfe_u32 v14, v13, 16, 1
	v_lshrrev_b32_e32 v16, 16, v10
	v_and_or_b32 v10, v15, s55, v12
	v_add3_u32 v13, v13, v14, s72
	v_lshl_add_u64 v[14:15], s[16:17], 0, v[24:25]
	v_add_co_u32_e32 v52, vcc, s1, v14
	v_and_or_b32 v12, v35, s55, v16
	v_and_or_b32 v13, v13, s55, v36
	v_addc_co_u32_e32 v53, vcc, 0, v15, vcc
	global_store_dwordx4 v[52:53], v[10:13], off
	v_mov_b64_e32 v[36:37], v[210:211]
	v_mov_b64_e32 v[38:39], v[212:213]
	v_mov_b64_e32 v[40:41], v[214:215]
	v_mov_b64_e32 v[42:43], v[216:217]
	v_mov_b64_e32 v[44:45], v[176:177]
	v_mov_b64_e32 v[46:47], v[178:179]
	v_mov_b64_e32 v[48:49], v[172:173]
	v_mov_b64_e32 v[50:51], v[174:175]
	v_mov_b64_e32 v[10:11], v[156:157]
	v_mov_b64_e32 v[12:13], v[158:159]
	v_mov_b64_e32 v[14:15], v[160:161]
	v_mov_b64_e32 v[16:17], v[162:163]
	v_pk_mul_f32 v[4:5], v[4:5], v[60:61] op_sel_hi:[1,0]
	v_pk_mul_f32 v[2:3], v[2:3], v[60:61] op_sel_hi:[1,0]
	v_pk_mul_f32 v[8:9], v[8:9], v[60:61] op_sel_hi:[1,0]
	v_pk_mul_f32 v[6:7], v[6:7], v[60:61] op_sel_hi:[1,0]
	v_lshl_add_u64 v[24:25], v[24:25], 0, s[14:15]
	global_load_dwordx4 v[124:127], v[228:229], off offset:-2048
	global_load_dwordx4 v[128:131], v[228:229], off offset:-2032
	global_load_dwordx4 v[132:135], v[228:229], off
	global_load_dwordx4 v[136:139], v[228:229], off offset:16
	s_cmp_lg_u32 s20, 0
	s_cbranch_scc0 .Lnorm_pf_nod_4
	global_load_dwordx4 v[140:143], v[230:231], off
	global_load_dwordx4 v[144:147], v[232:233], off
.Lnorm_pf_nod_4:
	s_ashr_i32 s14, s33, 12
	s_mul_i32 s14, s14, 0x3000
	s_add_u32 s34, s2, s14
	s_addc_u32 s35, s3, 0
	s_add_u32 s40, s34, 0x1000
	s_addc_u32 s41, s35, 0
	global_load_dwordx4 v[148:151], v0, s[40:41]
	global_load_dwordx4 v[152:155], v0, s[40:41] offset:16
	global_load_dwordx4 v[156:159], v0, s[40:41] offset:2048
	global_load_dwordx4 v[160:163], v0, s[40:41] offset:2064
	global_load_dwordx4 v[164:167], v0, s[34:35]
	global_load_dwordx4 v[168:171], v0, s[34:35] offset:16
	global_load_dwordx4 v[172:175], v0, s[34:35] offset:2048
	global_load_dwordx4 v[176:179], v0, s[34:35] offset:2064
	s_add_i32 s14, s33, s86
	s_cmp_lt_i32 s14, 0x8000
	s_cselect_b32 s33, s14, s33
	s_cselect_b64 s[14:15], s[28:29], 0
	v_lshl_add_u64 v[228:229], v[228:229], 0, s[14:15]
	s_cselect_b64 s[14:15], s[98:99], 0
	v_lshl_add_u64 v[230:231], v[230:231], 0, s[14:15]
	v_lshl_add_u64 v[232:233], v[232:233], 0, s[14:15]
	v_pk_add_f32 v[12:13], v[12:13], 1.0 op_sel_hi:[1,0]
	v_pk_add_f32 v[16:17], v[16:17], 1.0 op_sel_hi:[1,0]
	v_pk_add_f32 v[10:11], v[10:11], 1.0 op_sel_hi:[1,0]
	v_pk_add_f32 v[14:15], v[14:15], 1.0 op_sel_hi:[1,0]
	v_pk_mul_f32 v[6:7], v[36:37], v[6:7]
	v_pk_mul_f32 v[8:9], v[38:39], v[8:9]
	v_pk_mul_f32 v[2:3], v[40:41], v[2:3]
	v_pk_mul_f32 v[4:5], v[42:43], v[4:5]
	v_pk_fma_f32 v[2:3], v[14:15], v[2:3], v[44:45]
	v_pk_fma_f32 v[4:5], v[16:17], v[4:5], v[46:47]
	v_pk_fma_f32 v[8:9], v[12:13], v[8:9], v[50:51]
	v_pk_fma_f32 v[6:7], v[10:11], v[6:7], v[48:49]
	v_bfe_u32 v12, v8, 16, 1
	v_bfe_u32 v10, v6, 16, 1
	v_bfe_u32 v14, v2, 16, 1
	v_bfe_u32 v15, v3, 16, 1
	v_bfe_u32 v16, v4, 16, 1
	v_bfe_u32 v11, v7, 16, 1
	v_bfe_u32 v13, v9, 16, 1
	v_bfe_u32 v17, v5, 16, 1
	v_add3_u32 v6, v6, v10, s72
	v_add3_u32 v8, v8, v12, s72
	v_add3_u32 v2, v2, v14, s72
	v_add3_u32 v10, v3, v15, s72
	v_add3_u32 v3, v4, v16, s72
	v_add3_u32 v7, v7, v11, s72
	v_add3_u32 v9, v9, v13, s72
	v_add3_u32 v5, v5, v17, s72
	v_lshrrev_b32_e32 v4, 16, v6
	v_lshrrev_b32_e32 v6, 16, v8
	v_lshrrev_b32_e32 v8, 16, v2
	v_lshrrev_b32_e32 v11, 16, v3
	v_and_or_b32 v2, v7, s55, v4
	v_and_or_b32 v3, v9, s55, v6
	v_and_or_b32 v4, v10, s55, v8
	v_and_or_b32 v5, v5, s55, v11
	global_store_dwordx4 v[52:53], v[2:5], off offset:1024
	s_cmp_lt_i32 s0, 0x8000
	s_cbranch_scc1 .Lnorm_loop
.Lnorm_exit:
.LBB0_174:
	s_waitcnt vmcnt(0)
	s_barrier
	s_and_saveexec_b64 s[0:1], s[84:85]
	s_xor_b64 s[0:1], exec, s[0:1]
	s_cbranch_execz .LBB0_223
	v_readlane_b32 s2, v247, 28
	s_waitcnt vmcnt(0) expcnt(0) lgkmcnt(0)
	s_nop 0
	v_mov_b32_e32 v0, s2
	ds_read_b32 v3, v0
	v_readlane_b32 s2, v247, 29
	s_waitcnt lgkmcnt(0)
	v_cmp_ne_u32_e32 vcc, 0, v3
	v_mov_b32_e32 v0, s2
	ds_read_b32 v0, v0
	s_cbranch_vccnz .LBB0_190
	s_mov_b32 s2, 1
	s_branch .LBB0_178
